# static priority raise for waves 4-7 also inside the attention item (on top of HGRN priority raise and LayerNorm counted wait)
# baseline (speedup 1.0000x reference)
; __device__ __forceinline__ int opaque_tid() { int t = threadIdx.x; asm volatile("" : "+v"(t)); return t; }
; __device__ __forceinline__ void attn_item(const Params& p, int item, unsigned char* smem) {
;     const int tid = opaque_tid(), w = tid >> 6, lane = tid & 63, fr = lane & 15, fq = lane >> 4;
;     const int qt = 31 - (item >> 4), bh = item & 15, b = bh >> 2, h = bh & 3;
;     const int blk = qt >> 1, o = (qt & 1) * 128, q0 = blk * 256 + o;
;     const bf16_t* P = (const bf16_t*)(p.ws + OFF_H);
;     const bf16_t* Vt = (const bf16_t*)((unsigned char*)p.out + OUT_VT) + (size_t)bh * 128 * SEQ;
;     const float* kmean = (const float*)(p.ws + OFF_KMEAN) + (size_t)bh * 16 * 128;
;     bf16_t* Y = (bf16_t*)(p.ws + OFF_XB);
;     bf16_t* Ks = (bf16_t*)smem; bf16_t* Vs = (bf16_t*)(smem + 34816);
;     float* kms = (float*)(smem + 71680); float* gts = (float*)(smem + 79872);
;     unsigned* sels = (unsigned*)(smem + 88576); int* tiles = (int*)(smem + 89088); unsigned* um = (unsigned*)(smem + 89344);
;     const bf16_t* Pb = P + (size_t)b * SEQ * DIN;
;     bf16x8 Qf[4];
;     { const bf16_t* qrow = Pb + (size_t)(q0 + 16 * w + fr) * DIN + h * 128;
; #pragma unroll
;       for (int kk = 0; kk < 4; ++kk) Qf[kk] = *(const bf16x8*)(qrow + 32 * kk + 8 * fq); }
;     for (int i = tid; i < blk * 128; i += 512) kms[i] = kmean[i];
.LBB0_160:
	s_and_b64 vcc, exec, s[0:1]
	s_cbranch_vccz .LBB0_222
	v_lshrrev_b32_e32 v200, 6, v234
	s_nop 0
	v_readfirstlane_b32 s98, v200
	s_cmp_lt_u32 s98, 4
	s_cbranch_scc1 .Lat_noprio
	s_setprio 1
.Lat_noprio:
	s_add_i32 s8, s50, -16
	s_lshr_b32 s0, s8, 4
	s_xor_b32 s49, s0, 31
	s_lshl_b32 s0, s49, 7
	s_and_b32 s54, s0, 0x80
	s_lshl_b32 s0, s8, 10
	s_and_b32 s26, s0, 0x3000
	s_lshr_b32 s48, s49, 1
	s_mov_b32 s0, s26
	v_mov_b32_e32 v80, v234
	s_lshl_b32 s51, s48, 8
	v_writelane_b32 v255, s0, 52
	s_and_b32 s55, s50, 15
	s_or_b32 s2, s51, s54
	v_writelane_b32 v255, s1, 53
	s_mul_i32 s0, s26, 0x2c00
	v_readlane_b32 s26, v254, 50
	v_ashrrev_i32_e32 v82, 2, v80
	v_readlane_b32 s27, v254, 51
	s_add_u32 s56, s26, s0
	v_and_b32_e32 v156, -16, v82
	v_and_b32_e32 v154, 15, v80
	s_addc_u32 s57, s27, 0
	v_add_u32_e32 v155, s2, v156
	v_or_b32_e32 v100, v155, v154
	v_mov_b64_e32 v[0:1], s[56:57]
	v_mad_i64_i32 v[0:1], s[0:1], v100, s11, v[0:1]
	s_lshl_b32 s0, s8, 7
	s_and_b32 s0, s0, 0x180
	v_bfe_u32 v83, v80, 4, 2
	s_lshl_b32 s52, s0, 1
	s_mov_b32 s53, s3
	v_lshl_add_u64 v[0:1], v[0:1], 0, s[52:53]
	v_lshlrev_b32_e32 v102, 4, v83
	v_mov_b32_e32 v103, v173
	v_lshl_add_u64 v[12:13], v[0:1], 0, v[102:103]
	global_load_dwordx4 v[0:3], v[12:13], off
	global_load_dwordx4 v[4:7], v[12:13], off offset:64
	global_load_dwordx4 v[8:11], v[12:13], off offset:128
	s_nop 0
	global_load_dwordx4 v[12:15], v[12:13], off offset:192
	s_lshl_b32 s8, s48, 7
	v_cmp_gt_i32_e32 vcc, s8, v80
	s_and_saveexec_b64 s[0:1], vcc
	s_cbranch_execz .LBB0_169
	v_add_u32_e32 v81, 0x200, v80
	s_waitcnt vmcnt(0)
	v_max_i32_e32 v16, s8, v81
	v_xad_u32 v17, v80, -1, v16
	s_movk_i32 s26, 0x1ff
	s_lshl_b32 s9, s55, 13
	v_cmp_lt_u32_e32 vcc, s26, v17
	s_mov_b64 s[42:43], -1
	v_mov_b32_e32 v16, v80
	s_and_saveexec_b64 s[40:41], vcc
	s_cbranch_execz .LBB0_166
	v_lshrrev_b32_e32 v16, 9, v17
	v_readlane_b32 s26, v253, 49
	v_add_u32_e32 v18, 1, v16
	s_add_u32 s42, s26, s9
	v_readlane_b32 s26, v253, 50
	s_addc_u32 s43, s26, 0
	v_and_b32_e32 v19, 0xfffffe, v18
	s_add_i32 s26, 0, 0x12000
	v_lshl_add_u32 v20, v80, 2, s26
	s_mov_b64 s[44:45], 0
	v_mov_b32_e32 v21, v19
	v_mov_b64_e32 v[16:17], v[80:81]

; __device__ __forceinline__ unsigned cvt_pk_bf16(float lo, float hi) { unsigned r; asm volatile("v_cvt_pk_bf16_f32 %0, %1, %2" : "=v"(r) : "v"(lo), "v"(hi)); return r; }
; __device__ __forceinline__ void attn_item(const Params& p, int item, unsigned char* smem) {
;     ...
;     float l = l_run + __shfl_xor(l_run, 16); l += __shfl_xor(l, 32);
;     const float inv = 1.0f / l;
;     bf16_t* yrow = Y + ((size_t)b * SEQ + qpos) * DM + h * 128 + 4 * fq;
; #pragma unroll
;     for (int dt = 0; dt < 8; ++dt) { u32x2 w2; w2.x = cvt_pk_bf16(oacc[dt][0] * inv, oacc[dt][1] * inv); w2.y = cvt_pk_bf16(oacc[dt][2] * inv, oacc[dt][3] * inv); *(u32x2*)(yrow + 16 * dt) = w2; }
.LBB0_302:
	v_and_b32_e32 v1, 64, v239
	v_xor_b32_e32 v0, 16, v239
	v_add_u32_e32 v1, 64, v1
	v_cmp_lt_i32_e32 vcc, v0, v1
	v_xor_b32_e32 v2, 32, v239
	s_mov_b32 s53, s3
	v_cndmask_b32_e32 v0, v239, v0, vcc
	v_lshlrev_b32_e32 v0, 2, v0
	ds_bpermute_b32 v0, v0, v112
	v_cmp_lt_i32_e32 vcc, v2, v1
	s_waitcnt lgkmcnt(5)
	v_mov_b32_e32 v105, v173
	s_waitcnt lgkmcnt(0)
	v_add_f32_e32 v0, v112, v0
	v_cndmask_b32_e32 v1, v239, v2, vcc
	v_lshlrev_b32_e32 v1, 2, v1
	ds_bpermute_b32 v1, v1, v0
	s_waitcnt lgkmcnt(0)
	v_add_f32_e32 v0, v0, v1
	v_div_scale_f32 v1, s[0:1], v0, v0, 1.0
	v_rcp_f32_e32 v2, v1
	v_div_scale_f32 v3, vcc, 1.0, v0, 1.0
	v_readlane_b32 s0, v255, 52
	v_fma_f32 v4, -v1, v2, 1.0
	v_fmac_f32_e32 v2, v4, v2
	v_mul_f32_e32 v4, v3, v2
	v_fma_f32 v5, -v1, v4, v3
	v_fmac_f32_e32 v4, v5, v2
	v_readlane_b32 s1, v255, 53
	v_fma_f32 v1, -v1, v4, v3
	s_mov_b32 s1, s3
	v_div_fmas_f32 v1, v1, v2, v4
	v_div_fixup_f32 v4, v1, v0, 1.0
	v_lshl_add_u64 v[0:1], v[100:101], 0, s[0:1]
	v_readlane_b32 s0, v254, 42
	v_lshlrev_b64 v[0:1], 12, v[0:1]
	v_readlane_b32 s1, v254, 43
	v_mul_f32_e32 v2, v64, v4
	v_mul_f32_e32 v3, v65, v4
	v_lshl_add_u64 v[0:1], s[0:1], 0, v[0:1]
	v_lshl_add_u64 v[0:1], v[0:1], 0, s[52:53]
	v_cvt_pk_bf16_f32 v2, v2, v3
	v_mul_f32_e32 v3, v66, v4
	v_lshl_add_u64 v[0:1], v[0:1], 0, v[104:105]
	v_mul_f32_e32 v5, v67, v4
	v_cvt_pk_bf16_f32 v3, v3, v5
	global_store_dwordx2 v[0:1], v[2:3], off
	v_mul_f32_e32 v2, v68, v4
	v_mul_f32_e32 v3, v69, v4
	v_cvt_pk_bf16_f32 v2, v2, v3
	v_mul_f32_e32 v3, v70, v4
	v_mul_f32_e32 v5, v71, v4
	v_cvt_pk_bf16_f32 v3, v3, v5
	global_store_dwordx2 v[0:1], v[2:3], off offset:32
	v_mul_f32_e32 v2, v72, v4
	v_mul_f32_e32 v3, v73, v4
	v_cvt_pk_bf16_f32 v2, v2, v3
	v_mul_f32_e32 v3, v74, v4
	v_mul_f32_e32 v5, v75, v4
	v_cvt_pk_bf16_f32 v3, v3, v5
	global_store_dwordx2 v[0:1], v[2:3], off offset:64
	v_mul_f32_e32 v2, v76, v4
	v_mul_f32_e32 v3, v77, v4
	v_cvt_pk_bf16_f32 v2, v2, v3
	v_mul_f32_e32 v3, v78, v4
	v_mul_f32_e32 v5, v79, v4
	v_cvt_pk_bf16_f32 v3, v3, v5
	global_store_dwordx2 v[0:1], v[2:3], off offset:96
	v_mul_f32_e32 v2, v80, v4
	v_mul_f32_e32 v3, v81, v4
	v_cvt_pk_bf16_f32 v2, v2, v3
	v_mul_f32_e32 v3, v82, v4
	v_mul_f32_e32 v5, v83, v4
	v_cvt_pk_bf16_f32 v3, v3, v5
	global_store_dwordx2 v[0:1], v[2:3], off offset:128
	v_mul_f32_e32 v2, v84, v4
	v_mul_f32_e32 v3, v85, v4
	v_cvt_pk_bf16_f32 v2, v2, v3
	v_mul_f32_e32 v3, v86, v4
	v_mul_f32_e32 v5, v87, v4
	v_cvt_pk_bf16_f32 v3, v3, v5
	global_store_dwordx2 v[0:1], v[2:3], off offset:160
	v_mul_f32_e32 v2, v88, v4
	v_mul_f32_e32 v3, v89, v4
	v_cvt_pk_bf16_f32 v2, v2, v3
	v_mul_f32_e32 v3, v90, v4
	v_mul_f32_e32 v5, v91, v4
	v_cvt_pk_bf16_f32 v3, v3, v5
	global_store_dwordx2 v[0:1], v[2:3], off offset:192
	v_mul_f32_e32 v2, v92, v4
	v_mul_f32_e32 v3, v93, v4
	v_cvt_pk_bf16_f32 v2, v2, v3
	v_mul_f32_e32 v3, v94, v4
	v_readlane_b32 s52, v255, 46
	v_mul_f32_e32 v4, v95, v4
	v_cvt_pk_bf16_f32 v3, v3, v4
	global_store_dwordx2 v[0:1], v[2:3], off offset:224
	v_readlane_b32 s53, v255, 47
	s_setprio 0
	s_cbranch_execnz .LBB0_129
	s_branch .LBB0_224
